# non-temporal hint also on the mixer weight conversion inside the main GEMM phase and on the layer-0 residual (kernel input) loads
# baseline (speedup 1.0000x reference)
; #define LAS __attribute__((address_space(3)))
; __device__ __forceinline__ int otid(int wv0) { int t = (wv0 << 6) | olane(); asm volatile("" : "+v"(t)); return t; }
; __device__ __forceinline__ int obid() { int b = blockIdx.x; asm volatile("" : "+s"(b)); return b; }
; __device__ __forceinline__ int ogrid() { int g = gridDim.x; asm volatile("" : "+s"(g)); return g; }
; #define CVT_LOAD(t_) do { const int k0_ = ((t_) % nkt) * 64, n0_ = ((t_) / nkt) * 64; const int sn = srcmap(kind, n0_ + nl); \
;     _Pragma("unroll") for (int i = 0; i < 8; ++i) { const int kl = kb + 8 * i; v[i] = 0.f; \
;       if (sn >= 0) { v[i] = src[(size_t)(k0_ + kl) * Nsrc + sn]; if (kscale) v[i] *= kscale[k0_ + kl]; } } } while (0)
; #define PH(b) for (int rep_ = 0, nrep_ = (int)(((PH_MASK >> (b)) & 1) + ((REP_MASK >> (b)) & 1)); rep_ < nrep_; ++rep_)
; __device__ __forceinline__ void cvt_job(LAS unsigned char* lds, const float* src, bf16_t* dst, const float* kscale, int K, int Nsrc, int Ndst, int kind, int wv0, int bid_, int grd_) {
;   LAS float* tile = (LAS float*)lds;
;   const int tid = otid(wv0), nkt = K / 64, ntile = (Ndst / 64) * nkt;
;   if (bid_ < 0) return;
;   const int nl = tid & 63, kb = tid >> 6;
;   float v[8];
;     ...
;   if (bid_ < ntile) CVT_LOAD(bid_);
; __global__ void __launch_bounds__(512, 2) mega(Params p_unused) {
;     ...
;     PH(18) { const int G_ = ogrid(), b_ = obid(), extra = ((NTOK / 256) * (NHP / 256)) % G_;
;       cvt_mixer_b(p, l, lds, wv0, extra ? b_ - extra : b_, extra ? G_ - extra : G_); }
.LBB0_324:
	s_mov_b32 s0, s60
	s_abs_i32 s2, s0
	v_cvt_f32_u32_e32 v0, s2
	s_sub_i32 s3, 0, s2
	s_lshl_b32 s6, s48, 9
	s_ashr_i32 s49, s48, 31
	v_rcp_iflag_f32_e32 v0, v0
	s_ashr_i32 s7, s6, 31
	s_mov_b32 s1, s82
	v_mul_f32_e32 v0, 0x4f7ffffe, v0
	v_cvt_u32_f32_e32 v0, v0
	s_nop 0
	v_readfirstlane_b32 s4, v0
	s_mul_i32 s3, s3, s4
	s_mul_hi_u32 s3, s4, s3
	s_add_i32 s4, s4, s3
	s_mul_hi_u32 s3, s4, 0x480
	s_mul_i32 s3, s3, s2
	s_sub_i32 s3, 0x480, s3
	s_sub_i32 s4, s3, s2
	s_cmp_ge_u32 s3, s2
	s_cselect_b32 s3, s4, s3
	s_sub_i32 s4, s3, s2
	s_cmp_ge_u32 s3, s2
	s_cselect_b32 s2, s4, s3
	s_sub_i32 s25, s1, s2
	s_sub_i32 s24, s0, s2
	s_mov_b32 s0, -1
	s_cmp_gt_i32 s25, -1
	v_mbcnt_lo_u32_b32 v0, s0, 0
	v_mbcnt_hi_u32_b32 v0, s0, v0
	s_cselect_b64 s[8:9], -1, 0
	v_or_b32_e32 v16, s30, v0
	s_and_b64 vcc, exec, s[8:9]
	s_cbranch_vccz .LBB0_376
	s_load_dwordx2 s[0:1], s[54:55], 0x38
	s_load_dwordx2 s[4:5], s[54:55], 0x28
	s_mul_i32 s3, s48, 0x600000
	s_mul_hi_i32 s2, s48, 0x600000
	v_and_b32_e32 v14, 63, v16
	s_waitcnt lgkmcnt(0)
	s_add_u32 s12, s0, s3
	s_addc_u32 s13, s1, s2
	s_lshl_b64 s[0:1], s[6:7], 2
	s_add_u32 s14, s4, s0
	s_addc_u32 s15, s5, s1
	s_cmpk_lt_u32 s25, 0x180
	s_cselect_b64 s[16:17], -1, 0
	s_cmpk_gt_u32 s25, 0x17f
	v_ashrrev_i32_e32 v17, 6, v16
	s_cbranch_scc1 .LBB0_345
	s_lshl_b32 s0, s25, 3
	s_and_b32 s0, s0, 0xfc0
	v_or_b32_e32 v96, s0, v14
	v_mul_u32_u24_e32 v0, 0xaab, v96
	v_lshrrev_b32_e32 v0, 19, v0
	v_mul_lo_u16_e32 v0, 0xc0, v0
	v_sub_u16_e32 v0, v96, v0
	v_cmp_lt_u16_e32 vcc, s67, v0
	s_and_saveexec_b64 s[2:3], vcc
	v_add_u32_e32 v1, 0xffffff80, v0
	v_lshrrev_b32_e32 v2, 1, v1
	v_lshlrev_b32_e32 v1, 5, v1
	v_sub_u32_e32 v0, v96, v0
	v_and_b32_e32 v1, 32, v1
	v_add_u32_e32 v0, v0, v2
	v_add3_u32 v96, v0, v1, s63
	s_or_b64 exec, exec, s[2:3]
	s_lshl_b32 s0, s25, 6
	s_and_b32 s0, s0, 0x1c0
	v_add_u32_e32 v8, s0, v17
	v_lshl_add_u64 v[10:11], v[96:97], 2, s[12:13]
	v_mad_i64_i32 v[0:1], s[0:1], v8, s33, v[10:11]
	global_load_dword v0, v[0:1], off nt
	s_cmp_lg_u64 s[4:5], 0
	s_waitcnt vmcnt(0)
	v_ashrrev_i32_e32 v9, 31, v8
	s_cselect_b64 s[18:19], -1, 0
	s_cmp_eq_u64 s[4:5], 0
	v_lshl_add_u64 v[12:13], v[8:9], 2, s[14:15]
	s_cbranch_scc1 .LBB0_330
	global_load_dword v1, v[12:13], off nt
	s_waitcnt vmcnt(0)
	v_mul_f32_e32 v0, v0, v1
.LBB0_330:
	v_add_u32_e32 v1, 8, v8
	v_mad_i64_i32 v[2:3], s[0:1], v1, s33, v[10:11]
	global_load_dword v1, v[2:3], off nt
	v_cndmask_b32_e64 v2, 0, 1, s[18:19]
	v_cmp_ne_u32_e64 s[2:3], 1, v2
	s_andn2_b64 vcc, exec, s[18:19]
	s_cbranch_vccnz .LBB0_332
	global_load_dword v2, v[12:13], off offset:32
	s_waitcnt vmcnt(0)
	v_mul_f32_e32 v1, v1, v2
.LBB0_332:
	v_add_u32_e32 v2, 16, v8
	v_mad_i64_i32 v[2:3], s[0:1], v2, s33, v[10:11]
	global_load_dword v2, v[2:3], off nt
	s_and_b64 vcc, exec, s[2:3]
	s_cbranch_vccnz .LBB0_334
	global_load_dword v3, v[12:13], off offset:64
	s_waitcnt vmcnt(0)
	v_mul_f32_e32 v2, v2, v3
.LBB0_334:
	v_add_u32_e32 v3, 24, v8
	v_mad_i64_i32 v[4:5], s[0:1], v3, s33, v[10:11]
	global_load_dword v3, v[4:5], off nt
	s_and_b64 vcc, exec, s[2:3]
	s_cbranch_vccnz .LBB0_336
	global_load_dword v4, v[12:13], off offset:96
	s_waitcnt vmcnt(0)
	v_mul_f32_e32 v3, v3, v4
.LBB0_336:
	v_add_u32_e32 v4, 32, v8
	v_mad_i64_i32 v[4:5], s[0:1], v4, s33, v[10:11]
	global_load_dword v4, v[4:5], off nt
	s_and_b64 vcc, exec, s[2:3]
	s_cbranch_vccnz .LBB0_338
	global_load_dword v5, v[12:13], off offset:128
	s_waitcnt vmcnt(0)
	v_mul_f32_e32 v4, v4, v5
.LBB0_338:
	v_add_u32_e32 v5, 40, v8
	v_mad_i64_i32 v[6:7], s[0:1], v5, s33, v[10:11]
	global_load_dword v5, v[6:7], off nt
	s_and_b64 vcc, exec, s[2:3]
	s_cbranch_vccnz .LBB0_340
	global_load_dword v6, v[12:13], off offset:160
	s_waitcnt vmcnt(0)
	v_mul_f32_e32 v5, v5, v6
.LBB0_340:
	v_add_u32_e32 v6, 48, v8
	v_mad_i64_i32 v[6:7], s[0:1], v6, s33, v[10:11]
	global_load_dword v6, v[6:7], off nt
	s_and_b64 vcc, exec, s[2:3]
	s_cbranch_vccnz .LBB0_342
	global_load_dword v7, v[12:13], off offset:192
	s_waitcnt vmcnt(0)
	v_mul_f32_e32 v6, v6, v7
.LBB0_342:
	v_add_u32_e32 v7, 56, v8
	v_mad_i64_i32 v[8:9], s[0:1], v7, s33, v[10:11]
	global_load_dword v7, v[8:9], off nt
	s_and_b64 vcc, exec, s[2:3]
	s_cbranch_vccnz .LBB0_344
	global_load_dword v8, v[12:13], off offset:224
	s_waitcnt vmcnt(0)
	v_mul_f32_e32 v7, v7, v8

; #define CVT_LOAD(t_) do { const int k0_ = ((t_) % nkt) * 64, n0_ = ((t_) / nkt) * 64; const int sn = srcmap(kind, n0_ + nl); \
;     _Pragma("unroll") for (int i = 0; i < 8; ++i) { const int kl = kb + 8 * i; v[i] = 0.f; \
;       if (sn >= 0) { v[i] = src[(size_t)(k0_ + kl) * Nsrc + sn]; if (kscale) v[i] *= kscale[k0_ + kl]; } } } while (0)
; __device__ __forceinline__ void cvt_job(LAS unsigned char* lds, const float* src, bf16_t* dst, const float* kscale, int K, int Nsrc, int Ndst, int kind, int wv0, int bid_, int grd_) {
;     ...
;   if (bid_ < ntile) CVT_LOAD(bid_);
;   for (int t = bid_; t < ntile; t += grd_) {
;     const int k0 = (t % nkt) * 64, n0 = (t / nkt) * 64;
; #pragma unroll
;     for (int i = 0; i < 8; ++i) tile[(kb + 8 * i) * 65 + nl] = v[i];
;     __syncthreads();
;     if (t + grd_ < ntile) CVT_LOAD(t + grd_);
.LBB0_349:
	s_add_i32 s26, s27, s24
	s_cmpk_gt_i32 s26, 0x17f
	s_cselect_b64 s[20:21], -1, 0
	s_and_b64 vcc, exec, s[20:21]
	s_waitcnt vmcnt(1)
	ds_write_b32 v17, v0
	ds_write_b32 v17, v1 offset:2080
	ds_write_b32 v17, v2 offset:4160
	ds_write_b32 v17, v3 offset:6240
	ds_write_b32 v17, v4 offset:8320
	ds_write_b32 v17, v5 offset:10400
	ds_write_b32 v17, v6 offset:12480
	ds_write_b32 v17, v7 offset:14560
	s_waitcnt lgkmcnt(0)
	s_barrier
	s_cbranch_vccnz .LBB0_348
	s_ashr_i32 s2, s26, 31
	s_lshr_b32 s2, s2, 29
	s_add_i32 s2, s26, s2
	s_ashr_i32 s22, s2, 3
	v_lshl_or_b32 v96, s22, 6, v14
	v_mul_hi_i32 v0, v96, s71
	v_lshrrev_b32_e32 v1, 31, v0
	v_lshrrev_b32_e32 v0, 5, v0
	v_add_u32_e32 v0, v0, v1
	v_mul_lo_u32 v0, v0, s59
	v_sub_u32_e32 v0, v96, v0
	v_cmp_lt_i32_e32 vcc, s67, v0
	s_and_saveexec_b64 s[2:3], vcc
	v_add_u32_e32 v1, 0xffffff80, v0
	v_lshrrev_b32_e32 v2, 1, v1
	v_lshlrev_b32_e32 v1, 5, v1
	v_sub_u32_e32 v0, v96, v0
	v_and_b32_e32 v1, 32, v1
	v_add_u32_e32 v0, v0, v2
	v_add3_u32 v96, v0, v1, s63
	s_or_b64 exec, exec, s[2:3]
	v_add_u32_e32 v0, s0, v16
	s_lshl_b32 s2, s22, 9
	v_cndmask_b32_e64 v1, 0, 1, s[18:19]
	v_cmp_lt_i32_e64 s[4:5], -1, v96
	v_subrev_u32_e32 v10, s2, v0
	v_lshl_add_u64 v[12:13], v[96:97], 2, s[12:13]
	v_mov_b32_e32 v0, s93
	v_cmp_ne_u32_e64 s[2:3], 1, v1
	s_and_saveexec_b64 s[22:23], s[4:5]
	s_cbranch_execz .LBB0_355
	v_mad_i64_i32 v[0:1], s[28:29], v10, s33, v[12:13]
	global_load_dword v0, v[0:1], off nt
	s_and_b64 vcc, exec, s[2:3]
	s_cbranch_vccnz .LBB0_355
	v_ashrrev_i32_e32 v11, 31, v10
	v_lshl_add_u64 v[2:3], v[10:11], 2, s[14:15]
	global_load_dword v1, v[2:3], off nt
	s_waitcnt vmcnt(0)
	v_mul_f32_e32 v0, v0, v1
.LBB0_355:
	s_or_b64 exec, exec, s[22:23]
	v_mov_b32_e32 v1, s93
	s_and_saveexec_b64 s[22:23], s[4:5]
	s_cbranch_execz .LBB0_358
	v_add_u32_e32 v1, 8, v10
	v_mad_i64_i32 v[2:3], s[28:29], v1, s33, v[12:13]
	global_load_dword v1, v[2:3], off nt
	s_and_b64 vcc, exec, s[2:3]
	s_cbranch_vccnz .LBB0_358
	v_ashrrev_i32_e32 v11, 31, v10
	v_lshl_add_u64 v[2:3], v[10:11], 2, s[14:15]
	global_load_dword v2, v[2:3], off offset:32
	s_waitcnt vmcnt(0)
	v_mul_f32_e32 v1, v1, v2
.LBB0_358:
	s_or_b64 exec, exec, s[22:23]
	v_mov_b32_e32 v2, s93
	s_and_saveexec_b64 s[22:23], s[4:5]
	s_cbranch_execz .LBB0_361
	v_add_u32_e32 v2, 16, v10
	v_mad_i64_i32 v[2:3], s[28:29], v2, s33, v[12:13]
	global_load_dword v2, v[2:3], off nt
	s_and_b64 vcc, exec, s[2:3]
	s_cbranch_vccnz .LBB0_361
	v_ashrrev_i32_e32 v11, 31, v10
	v_lshl_add_u64 v[4:5], v[10:11], 2, s[14:15]
	global_load_dword v3, v[4:5], off offset:64
	s_waitcnt vmcnt(0)
	v_mul_f32_e32 v2, v2, v3
.LBB0_361:
	s_or_b64 exec, exec, s[22:23]
	v_mov_b32_e32 v3, s93
	s_and_saveexec_b64 s[22:23], s[4:5]
	s_cbranch_execz .LBB0_364
	v_add_u32_e32 v3, 24, v10
	v_mad_i64_i32 v[4:5], s[28:29], v3, s33, v[12:13]
	global_load_dword v3, v[4:5], off nt
	s_and_b64 vcc, exec, s[2:3]
	s_cbranch_vccnz .LBB0_364
	v_ashrrev_i32_e32 v11, 31, v10
	v_lshl_add_u64 v[4:5], v[10:11], 2, s[14:15]
	global_load_dword v4, v[4:5], off offset:96
	s_waitcnt vmcnt(0)
	v_mul_f32_e32 v3, v3, v4
.LBB0_364:
	s_or_b64 exec, exec, s[22:23]
	v_mov_b32_e32 v4, s93
	s_and_saveexec_b64 s[22:23], s[4:5]
	s_cbranch_execz .LBB0_367
	v_add_u32_e32 v4, 32, v10
	v_mad_i64_i32 v[4:5], s[28:29], v4, s33, v[12:13]
	global_load_dword v4, v[4:5], off nt
	s_and_b64 vcc, exec, s[2:3]
	s_cbranch_vccnz .LBB0_367
	v_ashrrev_i32_e32 v11, 31, v10
	v_lshl_add_u64 v[6:7], v[10:11], 2, s[14:15]
	global_load_dword v5, v[6:7], off offset:128
	s_waitcnt vmcnt(0)
	v_mul_f32_e32 v4, v4, v5
.LBB0_367:
	s_or_b64 exec, exec, s[22:23]
	v_mov_b32_e32 v5, s93
	s_and_saveexec_b64 s[22:23], s[4:5]
	s_cbranch_execz .LBB0_370
	v_add_u32_e32 v5, 40, v10
	v_mad_i64_i32 v[6:7], s[28:29], v5, s33, v[12:13]
	global_load_dword v5, v[6:7], off nt
	s_and_b64 vcc, exec, s[2:3]
	s_cbranch_vccnz .LBB0_370
	v_ashrrev_i32_e32 v11, 31, v10
	v_lshl_add_u64 v[6:7], v[10:11], 2, s[14:15]
	global_load_dword v6, v[6:7], off offset:160
	s_waitcnt vmcnt(0)
	v_mul_f32_e32 v5, v5, v6
; #define CVT_LOAD(t_) do { const int k0_ = ((t_) % nkt) * 64, n0_ = ((t_) / nkt) * 64; const int sn = srcmap(kind, n0_ + nl); \
;     _Pragma("unroll") for (int i = 0; i < 8; ++i) { const int kl = kb + 8 * i; v[i] = 0.f; \
;       if (sn >= 0) { v[i] = src[(size_t)(k0_ + kl) * Nsrc + sn]; if (kscale) v[i] *= kscale[k0_ + kl]; } } } while (0)
; __device__ __forceinline__ void cvt_job(LAS unsigned char* lds, const float* src, bf16_t* dst, const float* kscale, int K, int Nsrc, int Ndst, int kind, int wv0, int bid_, int grd_) {
;     ...
;   if (bid_ < ntile) CVT_LOAD(bid_);
; __device__ __forceinline__ void cvt_mixer_b(KP p, int l, LAS unsigned char* lds, int wv0, int f, int st) {
;     ...
;   cvt_job(lds, p->w_ukv + (size_t)l * 512 * NKV, (bf16_t*)(W + O_WUKV), p->kv_norm_g + l * 512, 512, NKV, NKV, 0, wv0, f, st);
.LBB0_370:
	s_or_b64 exec, exec, s[22:23]
	v_mov_b32_e32 v6, s93
	s_and_saveexec_b64 s[22:23], s[4:5]
	s_cbranch_execz .LBB0_373
	v_add_u32_e32 v6, 48, v10
	v_mad_i64_i32 v[6:7], s[28:29], v6, s33, v[12:13]
	global_load_dword v6, v[6:7], off nt
	s_and_b64 vcc, exec, s[2:3]
	s_cbranch_vccnz .LBB0_373
	v_ashrrev_i32_e32 v11, 31, v10
	v_lshl_add_u64 v[20:21], v[10:11], 2, s[14:15]
	global_load_dword v7, v[20:21], off offset:192
	s_waitcnt vmcnt(0)
	v_mul_f32_e32 v6, v6, v7
.LBB0_373:
	s_or_b64 exec, exec, s[22:23]
	v_mov_b32_e32 v7, s93
	s_and_saveexec_b64 s[22:23], s[4:5]
	s_cbranch_execz .LBB0_347
	v_add_u32_e32 v7, 56, v10
	v_mad_i64_i32 v[12:13], s[4:5], v7, s33, v[12:13]
	global_load_dword v7, v[12:13], off nt
	s_and_b64 vcc, exec, s[2:3]
	s_cbranch_vccnz .LBB0_347
	v_ashrrev_i32_e32 v11, 31, v10
	v_lshl_add_u64 v[10:11], v[10:11], 2, s[14:15]
	global_load_dword v9, v[10:11], off offset:224
	s_waitcnt vmcnt(0)
	v_mul_f32_e32 v7, v7, v9
	s_branch .LBB0_347
.LBB0_376:
	s_mov_b32 s0, -1
	s_andn2_b64 vcc, exec, s[8:9]
	s_waitcnt vmcnt(0)
	v_mbcnt_lo_u32_b32 v0, s0, 0
	v_mbcnt_hi_u32_b32 v0, s0, v0
	v_or_b32_e32 v12, s30, v0
	v_cndmask_b32_e64 v0, 0, 1, s[8:9]
	v_cmp_ne_u32_e64 s[2:3], 1, v0
	s_cbranch_vccnz .LBB0_430
	s_load_dwordx2 s[0:1], s[54:55], 0x40
	s_load_dwordx2 s[16:17], s[54:55], 0x30
	s_lshl_b64 s[4:5], s[48:49], 23
	v_and_b32_e32 v14, 63, v12
	v_ashrrev_i32_e32 v13, 6, v12
	s_waitcnt lgkmcnt(0)
	s_add_u32 s8, s0, s4
	s_addc_u32 s9, s1, s5
	s_lshl_b64 s[0:1], s[6:7], 2
	s_add_u32 s12, s16, s0
	s_addc_u32 s13, s17, s1
	s_cmpk_lt_u32 s25, 0x200
	s_cselect_b64 s[6:7], -1, 0
	s_cmpk_gt_u32 s25, 0x1ff
	s_cbranch_scc1 .LBB0_395
	s_lshl_b32 s0, s25, 6
	s_lshl_b32 s1, s25, 3
	s_and_b32 s0, s0, 0x1c0
	s_and_b32 s1, s1, 0xfc0
	v_or_b32_e32 v0, s1, v14
	v_add_u32_e32 v2, s0, v13
	v_lshlrev_b32_e32 v96, 2, v0
	v_ashrrev_i32_e32 v3, 31, v2
	v_lshl_add_u64 v[0:1], s[8:9], 0, v[96:97]
	v_lshlrev_b64 v[4:5], 14, v[2:3]
	v_lshl_add_u64 v[10:11], v[0:1], 0, v[4:5]
	global_load_dword v0, v[10:11], off nt
	s_cmp_lg_u64 s[16:17], 0
	s_cselect_b64 s[14:15], -1, 0
	s_cmp_eq_u64 s[16:17], 0
	v_lshl_add_u64 v[8:9], v[2:3], 2, s[12:13]
	s_cbranch_scc1 .LBB0_380
	global_load_dword v1, v[8:9], off nt
	s_waitcnt vmcnt(0)
	v_mul_f32_e32 v0, v0, v1
.LBB0_380:
	v_add_co_u32_e32 v2, vcc, 0x20000, v10
	s_nop 1
	v_addc_co_u32_e32 v3, vcc, 0, v11, vcc
	global_load_dword v1, v[2:3], off nt
	v_cndmask_b32_e64 v2, 0, 1, s[14:15]
	v_cmp_ne_u32_e64 s[4:5], 1, v2
	s_andn2_b64 vcc, exec, s[14:15]
	s_cbranch_vccnz .LBB0_382
	global_load_dword v2, v[8:9], off offset:32
	s_waitcnt vmcnt(0)
	v_mul_f32_e32 v1, v1, v2
.LBB0_382:
	v_add_co_u32_e32 v2, vcc, 0x40000, v10
	s_nop 1
	v_addc_co_u32_e32 v3, vcc, 0, v11, vcc
	global_load_dword v2, v[2:3], off nt
	s_and_b64 vcc, exec, s[4:5]
	s_cbranch_vccnz .LBB0_384
	global_load_dword v3, v[8:9], off offset:64
	s_waitcnt vmcnt(0)
	v_mul_f32_e32 v2, v2, v3
.LBB0_384:
	v_add_co_u32_e32 v4, vcc, 0x60000, v10
	s_nop 1
	v_addc_co_u32_e32 v5, vcc, 0, v11, vcc
	global_load_dword v3, v[4:5], off nt
	s_and_b64 vcc, exec, s[4:5]
	s_cbranch_vccnz .LBB0_386
	global_load_dword v4, v[8:9], off offset:96
	s_waitcnt vmcnt(0)
	v_mul_f32_e32 v3, v3, v4
.LBB0_386:
	v_add_co_u32_e32 v4, vcc, 0x80000, v10
	s_nop 1
	v_addc_co_u32_e32 v5, vcc, 0, v11, vcc
	global_load_dword v4, v[4:5], off nt
	s_and_b64 vcc, exec, s[4:5]
	s_cbranch_vccnz .LBB0_388
	global_load_dword v5, v[8:9], off offset:128
	s_waitcnt vmcnt(0)
	v_mul_f32_e32 v4, v4, v5
.LBB0_388:
	v_add_co_u32_e32 v6, vcc, 0xa0000, v10
	s_nop 1
	v_addc_co_u32_e32 v7, vcc, 0, v11, vcc
	global_load_dword v5, v[6:7], off nt
	s_and_b64 vcc, exec, s[4:5]
	s_cbranch_vccnz .LBB0_390
	global_load_dword v6, v[8:9], off offset:160
	s_waitcnt vmcnt(0)
	v_mul_f32_e32 v5, v5, v6
.LBB0_390:
	v_add_co_u32_e32 v6, vcc, 0xc0000, v10
	s_nop 1
	v_addc_co_u32_e32 v7, vcc, 0, v11, vcc
	global_load_dword v6, v[6:7], off nt
	s_and_b64 vcc, exec, s[4:5]
	s_cbranch_vccnz .LBB0_392
	global_load_dword v7, v[8:9], off offset:192
	s_waitcnt vmcnt(0)
	v_mul_f32_e32 v6, v6, v7
.LBB0_392:
	v_add_co_u32_e32 v10, vcc, 0xe0000, v10
	s_nop 1
	v_addc_co_u32_e32 v11, vcc, 0, v11, vcc
	global_load_dword v7, v[10:11], off nt
	s_and_b64 vcc, exec, s[4:5]
	s_cbranch_vccnz .LBB0_394
	global_load_dword v8, v[8:9], off offset:224
	s_waitcnt vmcnt(0)
	v_mul_f32_e32 v7, v7, v8

; #define CVT_LOAD(t_) do { const int k0_ = ((t_) % nkt) * 64, n0_ = ((t_) / nkt) * 64; const int sn = srcmap(kind, n0_ + nl); \
;     _Pragma("unroll") for (int i = 0; i < 8; ++i) { const int kl = kb + 8 * i; v[i] = 0.f; \
;       if (sn >= 0) { v[i] = src[(size_t)(k0_ + kl) * Nsrc + sn]; if (kscale) v[i] *= kscale[k0_ + kl]; } } } while (0)
; __device__ __forceinline__ void cvt_job(LAS unsigned char* lds, const float* src, bf16_t* dst, const float* kscale, int K, int Nsrc, int Ndst, int kind, int wv0, int bid_, int grd_) {
;     ...
;   for (int t = bid_; t < ntile; t += grd_) {
;     const int k0 = (t % nkt) * 64, n0 = (t / nkt) * 64;
; #pragma unroll
;     for (int i = 0; i < 8; ++i) tile[(kb + 8 * i) * 65 + nl] = v[i];
;     __syncthreads();
;     if (t + grd_ < ntile) CVT_LOAD(t + grd_);
.LBB0_399:
	s_add_i32 s22, s23, s24
	s_cmpk_gt_i32 s22, 0x1ff
	s_cselect_b64 s[18:19], -1, 0
	s_and_b64 vcc, exec, s[18:19]
	s_waitcnt vmcnt(1)
	ds_write_b32 v17, v0
	s_waitcnt vmcnt(6)
	ds_write_b32 v17, v1 offset:2080
	s_waitcnt vmcnt(5)
	ds_write_b32 v17, v2 offset:4160
	s_waitcnt vmcnt(4)
	ds_write_b32 v17, v3 offset:6240
	s_waitcnt vmcnt(3)
	ds_write_b32 v17, v4 offset:8320
	s_waitcnt vmcnt(2)
	ds_write_b32 v17, v5 offset:10400
	s_waitcnt vmcnt(1)
	ds_write_b32 v17, v6 offset:12480
	s_waitcnt vmcnt(0)
	ds_write_b32 v17, v7 offset:14560
	s_waitcnt lgkmcnt(0)
	s_barrier
	s_cbranch_vccnz .LBB0_398
	s_ashr_i32 s4, s22, 31
	s_lshr_b32 s4, s4, 29
	s_add_i32 s4, s22, s4
	s_ashr_i32 s4, s4, 3
	s_cmp_gt_i32 s22, -8
	v_lshl_or_b32 v96, s4, 6, v14
	s_cselect_b64 s[20:21], -1, 0
	s_lshl_b32 s4, s4, 9
	v_add_u32_e32 v0, s0, v16
	v_cndmask_b32_e64 v1, 0, 1, s[16:17]
	s_cmp_lt_i32 s22, -7
	v_subrev_u32_e32 v10, s4, v0
	v_lshl_add_u64 v[12:13], v[96:97], 2, s[8:9]
	v_mov_b32_e32 v0, s93
	v_cmp_ne_u32_e64 s[4:5], 1, v1
	s_cbranch_scc1 .LBB0_403
	v_ashrrev_i32_e32 v11, 31, v10
	v_lshlrev_b64 v[0:1], 14, v[10:11]
	v_lshl_add_u64 v[0:1], v[12:13], 0, v[0:1]
	global_load_dword v0, v[0:1], off nt
	s_and_b64 vcc, exec, s[4:5]
	s_cbranch_vccnz .LBB0_403
	v_lshl_add_u64 v[2:3], v[10:11], 2, s[12:13]
	global_load_dword v1, v[2:3], off nt
	s_waitcnt vmcnt(0)
	v_mul_f32_e32 v0, v0, v1
.LBB0_403:
	v_cndmask_b32_e64 v2, 0, 1, s[20:21]
	v_cmp_ne_u32_e64 s[6:7], 1, v2
	s_andn2_b64 vcc, exec, s[20:21]
	s_cbranch_vccnz .LBB0_422
	v_add_u32_e32 v2, 8, v10
	v_ashrrev_i32_e32 v3, 31, v2
	v_lshlrev_b64 v[2:3], 14, v[2:3]
	v_lshl_add_u64 v[2:3], v[12:13], 0, v[2:3]
	global_load_dword v1, v[2:3], off nt
	s_and_b64 vcc, exec, s[4:5]
	s_cbranch_vccnz .LBB0_406
	v_ashrrev_i32_e32 v11, 31, v10
	v_lshl_add_u64 v[2:3], v[10:11], 2, s[12:13]
	global_load_dword v2, v[2:3], off offset:32
	s_waitcnt vmcnt(0)
	v_mul_f32_e32 v1, v1, v2

.LBB0_407:
	v_add_u32_e32 v2, 16, v10
	v_ashrrev_i32_e32 v3, 31, v2
	v_lshlrev_b64 v[2:3], 14, v[2:3]
	v_lshl_add_u64 v[2:3], v[12:13], 0, v[2:3]
	global_load_dword v2, v[2:3], off nt
	s_and_b64 vcc, exec, s[4:5]
	s_cbranch_vccnz .LBB0_409
	v_ashrrev_i32_e32 v11, 31, v10
	v_lshl_add_u64 v[4:5], v[10:11], 2, s[12:13]
	global_load_dword v3, v[4:5], off offset:64
	s_waitcnt vmcnt(0)
	v_mul_f32_e32 v2, v2, v3

.LBB0_410:
	v_add_u32_e32 v4, 24, v10
	v_ashrrev_i32_e32 v5, 31, v4
	v_lshlrev_b64 v[4:5], 14, v[4:5]
	v_lshl_add_u64 v[4:5], v[12:13], 0, v[4:5]
	global_load_dword v3, v[4:5], off nt
	s_and_b64 vcc, exec, s[4:5]
	s_cbranch_vccnz .LBB0_412
	v_ashrrev_i32_e32 v11, 31, v10
	v_lshl_add_u64 v[4:5], v[10:11], 2, s[12:13]
	global_load_dword v4, v[4:5], off offset:96
	s_waitcnt vmcnt(0)
	v_mul_f32_e32 v3, v3, v4

.LBB0_413:
	v_add_u32_e32 v4, 32, v10
	v_ashrrev_i32_e32 v5, 31, v4
	v_lshlrev_b64 v[4:5], 14, v[4:5]
	v_lshl_add_u64 v[4:5], v[12:13], 0, v[4:5]
	global_load_dword v4, v[4:5], off nt
	s_and_b64 vcc, exec, s[4:5]
	s_cbranch_vccnz .LBB0_415
	v_ashrrev_i32_e32 v11, 31, v10
	v_lshl_add_u64 v[6:7], v[10:11], 2, s[12:13]
	global_load_dword v5, v[6:7], off offset:128
	s_waitcnt vmcnt(0)
	v_mul_f32_e32 v4, v4, v5

.LBB0_416:
	v_add_u32_e32 v6, 40, v10
	v_ashrrev_i32_e32 v7, 31, v6
	v_lshlrev_b64 v[6:7], 14, v[6:7]
	v_lshl_add_u64 v[6:7], v[12:13], 0, v[6:7]
	global_load_dword v5, v[6:7], off nt
	s_and_b64 vcc, exec, s[4:5]
	s_cbranch_vccnz .LBB0_418
	v_ashrrev_i32_e32 v11, 31, v10
	v_lshl_add_u64 v[6:7], v[10:11], 2, s[12:13]
	global_load_dword v6, v[6:7], off offset:160
	s_waitcnt vmcnt(0)
	v_mul_f32_e32 v5, v5, v6

.LBB0_419:
	v_add_u32_e32 v6, 48, v10
	v_ashrrev_i32_e32 v7, 31, v6
	v_lshlrev_b64 v[6:7], 14, v[6:7]
	v_lshl_add_u64 v[6:7], v[12:13], 0, v[6:7]
	global_load_dword v6, v[6:7], off nt
	s_and_b64 vcc, exec, s[4:5]
	s_cbranch_vccnz .LBB0_421
	v_ashrrev_i32_e32 v11, 31, v10
	v_lshl_add_u64 v[20:21], v[10:11], 2, s[12:13]
	global_load_dword v7, v[20:21], off offset:192
	s_waitcnt vmcnt(0)
	v_mul_f32_e32 v6, v6, v7

; #define CVT_LOAD(t_) do { const int k0_ = ((t_) % nkt) * 64, n0_ = ((t_) / nkt) * 64; const int sn = srcmap(kind, n0_ + nl); \
;     _Pragma("unroll") for (int i = 0; i < 8; ++i) { const int kl = kb + 8 * i; v[i] = 0.f; \
;       if (sn >= 0) { v[i] = src[(size_t)(k0_ + kl) * Nsrc + sn]; if (kscale) v[i] *= kscale[k0_ + kl]; } } } while (0)
; __device__ __forceinline__ void cvt_job(LAS unsigned char* lds, const float* src, bf16_t* dst, const float* kscale, int K, int Nsrc, int Ndst, int kind, int wv0, int bid_, int grd_) {
;     ...
;   if (bid_ < ntile) CVT_LOAD(bid_);
; __device__ __forceinline__ void cvt_mixer_b(KP p, int l, LAS unsigned char* lds, int wv0, int f, int st) {
;     ...
;   cvt_job(lds, p->w_proj_a + (size_t)l * 1024 * DM, (bf16_t*)(W + O_PA), nullptr, 1024, DM, DM, 0, wv0, f, st);
.LBB0_428:
	v_add_u32_e32 v20, 56, v10
	v_ashrrev_i32_e32 v21, 31, v20
	v_lshlrev_b64 v[20:21], 14, v[20:21]
	v_lshl_add_u64 v[12:13], v[12:13], 0, v[20:21]
	global_load_dword v7, v[12:13], off nt
	s_and_b64 vcc, exec, s[4:5]
	s_cbranch_vccnz .LBB0_398
	v_ashrrev_i32_e32 v11, 31, v10
	v_lshl_add_u64 v[10:11], v[10:11], 2, s[12:13]
	global_load_dword v9, v[10:11], off offset:224
	s_waitcnt vmcnt(0)
	v_mul_f32_e32 v7, v7, v9
	s_branch .LBB0_398
.LBB0_430:
	s_mov_b32 s0, -1
	s_lshl_b64 s[6:7], s[48:49], 21
	s_waitcnt vmcnt(0)
	v_mbcnt_lo_u32_b32 v0, s0, 0
	v_mbcnt_hi_u32_b32 v0, s0, v0
	v_or_b32_e32 v8, s30, v0
	s_and_b64 vcc, exec, s[2:3]
	s_cbranch_vccnz .LBB0_452
	s_cmpk_gt_u32 s25, 0x1ff
	s_cbranch_scc1 .LBB0_452
	s_load_dwordx2 s[0:1], s[54:55], 0x68
	s_lshl_b64 s[4:5], s[6:7], 2
	v_and_b32_e32 v14, 63, v8
	v_ashrrev_i32_e32 v9, 6, v8
	v_ashrrev_i32_e32 v15, 3, v8
	s_waitcnt lgkmcnt(0)
	s_add_u32 s8, s0, s4
	s_addc_u32 s9, s1, s5
	s_add_u32 s12, s10, 0x3100000
	s_addc_u32 s13, s11, 0
	s_lshl_b32 s0, s25, 6
	s_lshl_b32 s4, s25, 2
	s_and_b32 s1, s0, 0x3c0
	s_and_b32 s4, s4, 0x7c0
	v_or_b32_e32 v1, s4, v14
	v_add_u32_e32 v0, s1, v9
	v_lshlrev_b32_e32 v96, 2, v1
	v_ashrrev_i32_e32 v1, 31, v0
	v_lshl_add_u64 v[2:3], s[8:9], 0, v[96:97]
	v_lshlrev_b64 v[0:1], 13, v[0:1]
	v_lshl_add_u64 v[10:11], v[2:3], 0, v[0:1]
	s_mov_b32 s1, 0x10000
	v_add_co_u32_e32 v2, vcc, s1, v10
	s_mov_b32 s1, 0x20000
	s_nop 0
	v_addc_co_u32_e32 v3, vcc, 0, v11, vcc
	global_load_dword v0, v[10:11], off nt
	global_load_dword v1, v[2:3], off nt
	v_add_co_u32_e32 v2, vcc, s1, v10
	s_mov_b32 s1, 0x30000
	s_nop 0
	v_addc_co_u32_e32 v3, vcc, 0, v11, vcc
	v_add_co_u32_e32 v4, vcc, s1, v10
	s_mov_b32 s1, 0x40000
	s_nop 0
	v_addc_co_u32_e32 v5, vcc, 0, v11, vcc
	global_load_dword v2, v[2:3], off nt
	v_lshlrev_b32_e32 v8, 3, v8
	global_load_dword v3, v[4:5], off nt
	v_add_co_u32_e32 v4, vcc, s1, v10
	s_mov_b32 s1, 0x50000
	s_nop 0
	v_addc_co_u32_e32 v5, vcc, 0, v11, vcc
	v_add_co_u32_e32 v6, vcc, s1, v10
	s_mov_b32 s1, 0x60000
	s_nop 0
	v_addc_co_u32_e32 v7, vcc, 0, v11, vcc
	global_load_dword v4, v[4:5], off nt
	v_and_b32_e32 v8, 56, v8
	global_load_dword v5, v[6:7], off nt
	v_add_co_u32_e32 v6, vcc, s1, v10
	s_mov_b32 s1, 0x70000
	s_nop 0
	v_addc_co_u32_e32 v7, vcc, 0, v11, vcc
	v_add_co_u32_e32 v10, vcc, s1, v10
	global_load_dword v6, v[6:7], off nt
	s_nop 0
	v_addc_co_u32_e32 v11, vcc, 0, v11, vcc
	global_load_dword v7, v[10:11], off nt
	v_lshl_add_u32 v10, v14, 2, 0
	v_lshl_add_u32 v11, v15, 2, 0
	v_mul_u32_u24_e32 v12, 0x104, v8
	v_mul_lo_u32 v13, v9, s70
	s_lshl_b32 s1, s24, 6
	v_add_u32_e32 v16, s1, v9
	v_add_u32_e32 v17, v10, v13
	v_add_u32_e32 v18, v11, v12
	v_lshlrev_b32_e32 v8, 1, v8
	s_mov_b32 s19, s25
	s_branch .LBB0_435
.LBB0_433:
	v_add_u32_e32 v12, 56, v12
	v_ashrrev_i32_e32 v13, 31, v12
	v_lshlrev_b64 v[12:13], 13, v[12:13]
	v_lshl_add_u64 v[10:11], v[10:11], 0, v[12:13]
	global_load_dword v7, v[10:11], off nt

; #define CVT_LOAD(t_) do { const int k0_ = ((t_) % nkt) * 64, n0_ = ((t_) / nkt) * 64; const int sn = srcmap(kind, n0_ + nl); \
;     _Pragma("unroll") for (int i = 0; i < 8; ++i) { const int kl = kb + 8 * i; v[i] = 0.f; \
;       if (sn >= 0) { v[i] = src[(size_t)(k0_ + kl) * Nsrc + sn]; if (kscale) v[i] *= kscale[k0_ + kl]; } } } while (0)
; __device__ __forceinline__ void cvt_job(LAS unsigned char* lds, const float* src, bf16_t* dst, const float* kscale, int K, int Nsrc, int Ndst, int kind, int wv0, int bid_, int grd_) {
;     ...
;   for (int t = bid_; t < ntile; t += grd_) {
;     const int k0 = (t % nkt) * 64, n0 = (t / nkt) * 64;
; #pragma unroll
;     for (int i = 0; i < 8; ++i) tile[(kb + 8 * i) * 65 + nl] = v[i];
;     __syncthreads();
;     if (t + grd_ < ntile) CVT_LOAD(t + grd_);
.LBB0_435:
	s_add_i32 s18, s19, s24
	s_cmpk_gt_i32 s18, 0x1ff
	s_cselect_b64 s[14:15], -1, 0
	s_and_b64 vcc, exec, s[14:15]
	s_waitcnt vmcnt(1)
	ds_write_b32 v17, v0
	s_waitcnt vmcnt(6)
	ds_write_b32 v17, v1 offset:2080
	s_waitcnt vmcnt(5)
	ds_write_b32 v17, v2 offset:4160
	s_waitcnt vmcnt(4)
	ds_write_b32 v17, v3 offset:6240
	s_waitcnt vmcnt(3)
	ds_write_b32 v17, v4 offset:8320
	s_waitcnt vmcnt(2)
	ds_write_b32 v17, v5 offset:10400
	s_waitcnt vmcnt(1)
	ds_write_b32 v17, v6 offset:12480
	s_waitcnt vmcnt(0)
	ds_write_b32 v17, v7 offset:14560
	s_waitcnt lgkmcnt(0)
	s_barrier
	s_cbranch_vccnz .LBB0_434
	s_ashr_i32 s4, s18, 31
	s_lshr_b32 s4, s4, 28
	s_add_i32 s4, s18, s4
	s_ashr_i32 s4, s4, 4
	s_cmp_gt_i32 s18, -16
	v_lshl_or_b32 v96, s4, 6, v14
	s_cselect_b64 s[16:17], -1, 0
	s_lshl_b32 s4, s4, 10
	v_add_u32_e32 v0, s0, v16
	s_cmp_lt_i32 s18, -15
	v_subrev_u32_e32 v12, s4, v0
	v_lshl_add_u64 v[10:11], v[96:97], 2, s[8:9]
	v_mov_b32_e32 v0, s93
	s_cbranch_scc1 .LBB0_438
	v_ashrrev_i32_e32 v13, 31, v12
	v_lshlrev_b64 v[0:1], 13, v[12:13]
	v_lshl_add_u64 v[0:1], v[10:11], 0, v[0:1]
	global_load_dword v0, v[0:1], off nt
.LBB0_438:
	v_cndmask_b32_e64 v2, 0, 1, s[16:17]
	v_cmp_ne_u32_e64 s[4:5], 1, v2
	s_andn2_b64 vcc, exec, s[16:17]
	s_cbranch_vccnz .LBB0_445
	v_add_u32_e32 v2, 8, v12
	v_ashrrev_i32_e32 v3, 31, v2
	v_lshlrev_b64 v[2:3], 13, v[2:3]
	v_lshl_add_u64 v[2:3], v[10:11], 0, v[2:3]
	global_load_dword v1, v[2:3], off nt
	s_and_b64 vcc, exec, s[4:5]
	s_cbranch_vccz .LBB0_446

.LBB0_446:
	v_add_u32_e32 v2, 16, v12
	v_ashrrev_i32_e32 v3, 31, v2
	v_lshlrev_b64 v[2:3], 13, v[2:3]
	v_lshl_add_u64 v[2:3], v[10:11], 0, v[2:3]
	global_load_dword v2, v[2:3], off nt
	s_and_b64 vcc, exec, s[4:5]
	s_cbranch_vccnz .LBB0_441
.LBB0_447:
	v_add_u32_e32 v4, 24, v12
	v_ashrrev_i32_e32 v5, 31, v4
	v_lshlrev_b64 v[4:5], 13, v[4:5]
	v_lshl_add_u64 v[4:5], v[10:11], 0, v[4:5]
	global_load_dword v3, v[4:5], off nt
	s_and_b64 vcc, exec, s[4:5]
	s_cbranch_vccnz .LBB0_442
.LBB0_448:
	v_add_u32_e32 v4, 32, v12
	v_ashrrev_i32_e32 v5, 31, v4
	v_lshlrev_b64 v[4:5], 13, v[4:5]
	v_lshl_add_u64 v[4:5], v[10:11], 0, v[4:5]
	global_load_dword v4, v[4:5], off nt
	s_and_b64 vcc, exec, s[4:5]
	s_cbranch_vccnz .LBB0_443
.LBB0_449:
	v_add_u32_e32 v6, 40, v12
	v_ashrrev_i32_e32 v7, 31, v6
	v_lshlrev_b64 v[6:7], 13, v[6:7]
	v_lshl_add_u64 v[6:7], v[10:11], 0, v[6:7]
	global_load_dword v5, v[6:7], off nt
	s_and_b64 vcc, exec, s[4:5]
	s_cbranch_vccnz .LBB0_444
.LBB0_450:
	v_add_u32_e32 v6, 48, v12
	v_ashrrev_i32_e32 v7, 31, v6
	v_lshlrev_b64 v[6:7], 13, v[6:7]
	v_lshl_add_u64 v[6:7], v[10:11], 0, v[6:7]
	global_load_dword v6, v[6:7], off nt
	s_and_b64 vcc, exec, s[4:5]
	s_cbranch_vccz .LBB0_433

; #define LAS __attribute__((address_space(3)))
; __device__ __forceinline__ int otid(int wv0) { int t = (wv0 << 6) | olane(); asm volatile("" : "+v"(t)); return t; }
; #define CVT_LOAD(t_) do { const int k0_ = ((t_) % nkt) * 64, n0_ = ((t_) / nkt) * 64; const int sn = srcmap(kind, n0_ + nl); \
;     _Pragma("unroll") for (int i = 0; i < 8; ++i) { const int kl = kb + 8 * i; v[i] = 0.f; \
;       if (sn >= 0) { v[i] = src[(size_t)(k0_ + kl) * Nsrc + sn]; if (kscale) v[i] *= kscale[k0_ + kl]; } } } while (0)
; __device__ __forceinline__ void cvt_job(LAS unsigned char* lds, const float* src, bf16_t* dst, const float* kscale, int K, int Nsrc, int Ndst, int kind, int wv0, int bid_, int grd_) {
;   LAS float* tile = (LAS float*)lds;
;   const int tid = otid(wv0), nkt = K / 64, ntile = (Ndst / 64) * nkt;
;   if (bid_ < 0) return;
;   const int nl = tid & 63, kb = tid >> 6;
;   float v[8];
;     ...
;   if (bid_ < ntile) CVT_LOAD(bid_);
; __device__ __forceinline__ void cvt_mixer_b(KP p, int l, LAS unsigned char* lds, int wv0, int f, int st) {
;     ...
;   cvt_job(lds, p->w_proj_b + (size_t)l * 2048 * DM, (bf16_t*)(W + O_PB), nullptr, 2048, DM, DM, 0, wv0, f, st);
.LBB0_452:
	s_mov_b32 s0, -1
	s_lshl_b64 s[8:9], s[48:49], 22
	s_waitcnt vmcnt(0)
	v_mbcnt_lo_u32_b32 v0, s0, 0
	v_mbcnt_hi_u32_b32 v0, s0, v0
	v_or_b32_e32 v8, s30, v0
	s_and_b64 vcc, exec, s[2:3]
	s_cbranch_vccnz .LBB0_474
	s_cmpk_gt_u32 s25, 0x3ff
	s_cbranch_scc1 .LBB0_474
	s_load_dwordx2 s[0:1], s[54:55], 0x70
	s_lshl_b64 s[4:5], s[8:9], 2
	v_and_b32_e32 v14, 63, v8
	v_ashrrev_i32_e32 v9, 6, v8
	v_ashrrev_i32_e32 v15, 3, v8
	s_waitcnt lgkmcnt(0)
	s_add_u32 s12, s0, s4
	s_addc_u32 s13, s1, s5
	s_add_u32 s14, s10, 0x3500000
	s_addc_u32 s15, s11, 0
	s_lshl_b32 s0, s25, 6
	s_lshl_b32 s4, s25, 1
	s_and_b32 s1, s0, 0x7c0
	s_and_b32 s4, s4, 0x7c0
	v_or_b32_e32 v1, s4, v14
	v_add_u32_e32 v0, s1, v9
	v_lshlrev_b32_e32 v96, 2, v1
	v_ashrrev_i32_e32 v1, 31, v0
	v_lshl_add_u64 v[2:3], s[12:13], 0, v[96:97]
	v_lshlrev_b64 v[0:1], 13, v[0:1]
	v_lshl_add_u64 v[10:11], v[2:3], 0, v[0:1]
	s_mov_b32 s1, 0x10000
	v_add_co_u32_e32 v2, vcc, s1, v10
	s_mov_b32 s1, 0x20000
	s_nop 0
	v_addc_co_u32_e32 v3, vcc, 0, v11, vcc
	global_load_dword v0, v[10:11], off nt
	global_load_dword v1, v[2:3], off nt
	v_add_co_u32_e32 v2, vcc, s1, v10
	s_mov_b32 s1, 0x30000
	s_nop 0
	v_addc_co_u32_e32 v3, vcc, 0, v11, vcc
	v_add_co_u32_e32 v4, vcc, s1, v10
	s_mov_b32 s1, 0x40000
	s_nop 0
	v_addc_co_u32_e32 v5, vcc, 0, v11, vcc
	global_load_dword v2, v[2:3], off nt
	v_lshlrev_b32_e32 v8, 3, v8
	global_load_dword v3, v[4:5], off nt
	v_add_co_u32_e32 v4, vcc, s1, v10
	s_mov_b32 s1, 0x50000
	s_nop 0
	v_addc_co_u32_e32 v5, vcc, 0, v11, vcc
	v_add_co_u32_e32 v6, vcc, s1, v10
	s_mov_b32 s1, 0x60000
	s_nop 0
	v_addc_co_u32_e32 v7, vcc, 0, v11, vcc
	global_load_dword v4, v[4:5], off nt
	v_and_b32_e32 v8, 56, v8
	global_load_dword v5, v[6:7], off nt
	v_add_co_u32_e32 v6, vcc, s1, v10
	s_mov_b32 s1, 0x70000
	s_nop 0
	v_addc_co_u32_e32 v7, vcc, 0, v11, vcc
	v_add_co_u32_e32 v10, vcc, s1, v10
	global_load_dword v6, v[6:7], off nt
	s_nop 0
	v_addc_co_u32_e32 v11, vcc, 0, v11, vcc
	global_load_dword v7, v[10:11], off nt
	v_lshl_add_u32 v10, v14, 2, 0
	v_lshl_add_u32 v11, v15, 2, 0
	v_mul_u32_u24_e32 v12, 0x104, v8
	v_mul_lo_u32 v13, v9, s70
	s_lshl_b32 s1, s24, 6
	v_add_u32_e32 v16, s1, v9
	v_add_u32_e32 v17, v10, v13
	v_add_u32_e32 v18, v11, v12
	v_lshlrev_b32_e32 v8, 1, v8
	s_mov_b32 s21, s25
	s_branch .LBB0_457

; #define CVT_LOAD(t_) do { const int k0_ = ((t_) % nkt) * 64, n0_ = ((t_) / nkt) * 64; const int sn = srcmap(kind, n0_ + nl); \
;     _Pragma("unroll") for (int i = 0; i < 8; ++i) { const int kl = kb + 8 * i; v[i] = 0.f; \
;       if (sn >= 0) { v[i] = src[(size_t)(k0_ + kl) * Nsrc + sn]; if (kscale) v[i] *= kscale[k0_ + kl]; } } } while (0)
; __device__ __forceinline__ void cvt_job(LAS unsigned char* lds, const float* src, bf16_t* dst, const float* kscale, int K, int Nsrc, int Ndst, int kind, int wv0, int bid_, int grd_) {
;     ...
;   for (int t = bid_; t < ntile; t += grd_) {
;     const int k0 = (t % nkt) * 64, n0 = (t / nkt) * 64;
; #pragma unroll
;     for (int i = 0; i < 8; ++i) tile[(kb + 8 * i) * 65 + nl] = v[i];
;     __syncthreads();
;     if (t + grd_ < ntile) CVT_LOAD(t + grd_);
.LBB0_457:
	s_add_i32 s20, s21, s24
	s_cmpk_gt_i32 s20, 0x3ff
	s_cselect_b64 s[16:17], -1, 0
	s_and_b64 vcc, exec, s[16:17]
	s_waitcnt vmcnt(1)
	ds_write_b32 v17, v0
	s_waitcnt vmcnt(6)
	ds_write_b32 v17, v1 offset:2080
	s_waitcnt vmcnt(5)
	ds_write_b32 v17, v2 offset:4160
	s_waitcnt vmcnt(4)
	ds_write_b32 v17, v3 offset:6240
	s_waitcnt vmcnt(3)
	ds_write_b32 v17, v4 offset:8320
	s_waitcnt vmcnt(2)
	ds_write_b32 v17, v5 offset:10400
	s_waitcnt vmcnt(1)
	ds_write_b32 v17, v6 offset:12480
	s_waitcnt vmcnt(0)
	ds_write_b32 v17, v7 offset:14560
	s_waitcnt lgkmcnt(0)
	s_barrier
	s_cbranch_vccnz .LBB0_456
	s_ashr_i32 s4, s20, 31
	s_lshr_b32 s4, s4, 27
	s_add_i32 s4, s20, s4
	s_ashr_i32 s4, s4, 5
	s_cmpk_gt_i32 s20, 0xffe0
	v_lshl_or_b32 v96, s4, 6, v14
	s_cselect_b64 s[18:19], -1, 0
	s_lshl_b32 s4, s4, 11
	v_add_u32_e32 v0, s0, v16
	s_cmpk_lt_i32 s20, 0xffe1
	v_subrev_u32_e32 v12, s4, v0
	v_lshl_add_u64 v[10:11], v[96:97], 2, s[12:13]
	v_mov_b32_e32 v0, s93
	s_cbranch_scc1 .LBB0_460
	v_ashrrev_i32_e32 v13, 31, v12
	v_lshlrev_b64 v[0:1], 13, v[12:13]
	v_lshl_add_u64 v[0:1], v[10:11], 0, v[0:1]
	global_load_dword v0, v[0:1], off nt
.LBB0_460:
	v_cndmask_b32_e64 v2, 0, 1, s[18:19]
	v_cmp_ne_u32_e64 s[4:5], 1, v2
	s_andn2_b64 vcc, exec, s[18:19]
	s_cbranch_vccnz .LBB0_467
	v_add_u32_e32 v2, 8, v12
	v_ashrrev_i32_e32 v3, 31, v2
	v_lshlrev_b64 v[2:3], 13, v[2:3]
	v_lshl_add_u64 v[2:3], v[10:11], 0, v[2:3]
	global_load_dword v1, v[2:3], off nt
	s_and_b64 vcc, exec, s[4:5]
	s_cbranch_vccz .LBB0_468

; #define LAS __attribute__((address_space(3)))
; __device__ __forceinline__ int otid(int wv0) { int t = (wv0 << 6) | olane(); asm volatile("" : "+v"(t)); return t; }
; #define CVT_LOAD(t_) do { const int k0_ = ((t_) % nkt) * 64, n0_ = ((t_) / nkt) * 64; const int sn = srcmap(kind, n0_ + nl); \
;     _Pragma("unroll") for (int i = 0; i < 8; ++i) { const int kl = kb + 8 * i; v[i] = 0.f; \
;       if (sn >= 0) { v[i] = src[(size_t)(k0_ + kl) * Nsrc + sn]; if (kscale) v[i] *= kscale[k0_ + kl]; } } } while (0)
; __device__ __forceinline__ void cvt_job(LAS unsigned char* lds, const float* src, bf16_t* dst, const float* kscale, int K, int Nsrc, int Ndst, int kind, int wv0, int bid_, int grd_) {
;   LAS float* tile = (LAS float*)lds;
;   const int tid = otid(wv0), nkt = K / 64, ntile = (Ndst / 64) * nkt;
;   if (bid_ < 0) return;
;   const int nl = tid & 63, kb = tid >> 6;
;   float v[8];
;     ...
;   if (bid_ < ntile) CVT_LOAD(bid_);
; __device__ __forceinline__ void cvt_mixer_b(KP p, int l, LAS unsigned char* lds, int wv0, int f, int st) {
;     ...
;   cvt_job(lds, p->w_proj_c + (size_t)l * 1024 * DM, (bf16_t*)(W + O_PC), nullptr, 1024, DM, DM, 0, wv0, f, st);
.LBB0_474:
	s_mov_b32 s0, -1
	s_and_b64 vcc, exec, s[2:3]
	s_waitcnt vmcnt(0)
	v_mbcnt_lo_u32_b32 v0, s0, 0
	v_mbcnt_hi_u32_b32 v0, s0, v0
	v_or_b32_e32 v8, s30, v0
	s_cbranch_vccnz .LBB0_496
	s_cmpk_gt_u32 s25, 0x1ff
	s_cbranch_scc1 .LBB0_496
	s_load_dwordx2 s[0:1], s[54:55], 0x78
	s_lshl_b64 s[4:5], s[6:7], 2
	v_and_b32_e32 v14, 63, v8
	v_ashrrev_i32_e32 v9, 6, v8
	v_ashrrev_i32_e32 v15, 3, v8
	s_waitcnt lgkmcnt(0)
	s_add_u32 s6, s0, s4
	s_addc_u32 s7, s1, s5
	s_add_u32 s12, s10, 0x3d00000
	s_addc_u32 s13, s11, 0
	s_lshl_b32 s0, s25, 6
	s_lshl_b32 s4, s25, 2
	s_and_b32 s1, s0, 0x3c0
	s_and_b32 s4, s4, 0x7c0
	v_or_b32_e32 v1, s4, v14
	v_add_u32_e32 v0, s1, v9
	v_lshlrev_b32_e32 v96, 2, v1
	v_ashrrev_i32_e32 v1, 31, v0
	v_lshl_add_u64 v[2:3], s[6:7], 0, v[96:97]
	v_lshlrev_b64 v[0:1], 13, v[0:1]
	v_lshl_add_u64 v[10:11], v[2:3], 0, v[0:1]
	s_mov_b32 s1, 0x10000
	v_add_co_u32_e32 v2, vcc, s1, v10
	s_mov_b32 s1, 0x20000
	s_nop 0
	v_addc_co_u32_e32 v3, vcc, 0, v11, vcc
	global_load_dword v0, v[10:11], off nt
	global_load_dword v1, v[2:3], off nt
	v_add_co_u32_e32 v2, vcc, s1, v10
	s_mov_b32 s1, 0x30000
	s_nop 0
	v_addc_co_u32_e32 v3, vcc, 0, v11, vcc
	v_add_co_u32_e32 v4, vcc, s1, v10
	s_mov_b32 s1, 0x40000
	s_nop 0
	v_addc_co_u32_e32 v5, vcc, 0, v11, vcc
	global_load_dword v2, v[2:3], off nt
	v_lshlrev_b32_e32 v8, 3, v8
	global_load_dword v3, v[4:5], off nt
	v_add_co_u32_e32 v4, vcc, s1, v10
	s_mov_b32 s1, 0x50000
	s_nop 0
	v_addc_co_u32_e32 v5, vcc, 0, v11, vcc
	v_add_co_u32_e32 v6, vcc, s1, v10
	s_mov_b32 s1, 0x60000
	s_nop 0
	v_addc_co_u32_e32 v7, vcc, 0, v11, vcc
	global_load_dword v4, v[4:5], off nt
	v_and_b32_e32 v8, 56, v8
	global_load_dword v5, v[6:7], off nt
	v_add_co_u32_e32 v6, vcc, s1, v10
	s_mov_b32 s1, 0x70000
	s_nop 0
	v_addc_co_u32_e32 v7, vcc, 0, v11, vcc
	v_add_co_u32_e32 v10, vcc, s1, v10
	global_load_dword v6, v[6:7], off nt
	s_nop 0
	v_addc_co_u32_e32 v11, vcc, 0, v11, vcc
	global_load_dword v7, v[10:11], off nt
	v_lshl_add_u32 v10, v14, 2, 0
	v_lshl_add_u32 v11, v15, 2, 0
	v_mul_u32_u24_e32 v12, 0x104, v8
	v_mul_lo_u32 v13, v9, s70
	s_lshl_b32 s1, s24, 6
	v_add_u32_e32 v16, s1, v9
	v_add_u32_e32 v17, v10, v13
	v_add_u32_e32 v18, v11, v12
	v_lshlrev_b32_e32 v8, 1, v8
	s_mov_b32 s19, s25
	s_branch .LBB0_479

; #define CVT_LOAD(t_) do { const int k0_ = ((t_) % nkt) * 64, n0_ = ((t_) / nkt) * 64; const int sn = srcmap(kind, n0_ + nl); \
;     _Pragma("unroll") for (int i = 0; i < 8; ++i) { const int kl = kb + 8 * i; v[i] = 0.f; \
;       if (sn >= 0) { v[i] = src[(size_t)(k0_ + kl) * Nsrc + sn]; if (kscale) v[i] *= kscale[k0_ + kl]; } } } while (0)
; __device__ __forceinline__ void cvt_job(LAS unsigned char* lds, const float* src, bf16_t* dst, const float* kscale, int K, int Nsrc, int Ndst, int kind, int wv0, int bid_, int grd_) {
;     ...
;   for (int t = bid_; t < ntile; t += grd_) {
;     const int k0 = (t % nkt) * 64, n0 = (t / nkt) * 64;
; #pragma unroll
;     for (int i = 0; i < 8; ++i) tile[(kb + 8 * i) * 65 + nl] = v[i];
;     __syncthreads();
;     if (t + grd_ < ntile) CVT_LOAD(t + grd_);
.LBB0_479:
	s_add_i32 s18, s19, s24
	s_cmpk_gt_i32 s18, 0x1ff
	s_cselect_b64 s[14:15], -1, 0
	s_and_b64 vcc, exec, s[14:15]
	s_waitcnt vmcnt(1)
	ds_write_b32 v17, v0
	s_waitcnt vmcnt(6)
	ds_write_b32 v17, v1 offset:2080
	s_waitcnt vmcnt(5)
	ds_write_b32 v17, v2 offset:4160
	s_waitcnt vmcnt(4)
	ds_write_b32 v17, v3 offset:6240
	s_waitcnt vmcnt(3)
	ds_write_b32 v17, v4 offset:8320
	s_waitcnt vmcnt(2)
	ds_write_b32 v17, v5 offset:10400
	s_waitcnt vmcnt(1)
	ds_write_b32 v17, v6 offset:12480
	s_waitcnt vmcnt(0)
	ds_write_b32 v17, v7 offset:14560
	s_waitcnt lgkmcnt(0)
	s_barrier
	s_cbranch_vccnz .LBB0_478
	s_ashr_i32 s4, s18, 31
	s_lshr_b32 s4, s4, 28
	s_add_i32 s4, s18, s4
	s_ashr_i32 s4, s4, 4
	s_cmp_gt_i32 s18, -16
	v_lshl_or_b32 v96, s4, 6, v14
	s_cselect_b64 s[16:17], -1, 0
	s_lshl_b32 s4, s4, 10
	v_add_u32_e32 v0, s0, v16
	s_cmp_lt_i32 s18, -15
	v_subrev_u32_e32 v12, s4, v0
	v_lshl_add_u64 v[10:11], v[96:97], 2, s[6:7]
	v_mov_b32_e32 v0, s93
	s_cbranch_scc1 .LBB0_482
	v_ashrrev_i32_e32 v13, 31, v12
	v_lshlrev_b64 v[0:1], 13, v[12:13]
	v_lshl_add_u64 v[0:1], v[10:11], 0, v[0:1]
	global_load_dword v0, v[0:1], off nt

; #define LAS __attribute__((address_space(3)))
; __device__ __forceinline__ int otid(int wv0) { int t = (wv0 << 6) | olane(); asm volatile("" : "+v"(t)); return t; }
; #define CVT_LOAD(t_) do { const int k0_ = ((t_) % nkt) * 64, n0_ = ((t_) / nkt) * 64; const int sn = srcmap(kind, n0_ + nl); \
;     _Pragma("unroll") for (int i = 0; i < 8; ++i) { const int kl = kb + 8 * i; v[i] = 0.f; \
;       if (sn >= 0) { v[i] = src[(size_t)(k0_ + kl) * Nsrc + sn]; if (kscale) v[i] *= kscale[k0_ + kl]; } } } while (0)
; __device__ __forceinline__ void cvt_job(LAS unsigned char* lds, const float* src, bf16_t* dst, const float* kscale, int K, int Nsrc, int Ndst, int kind, int wv0, int bid_, int grd_) {
;   LAS float* tile = (LAS float*)lds;
;   const int tid = otid(wv0), nkt = K / 64, ntile = (Ndst / 64) * nkt;
;   if (bid_ < 0) return;
;   const int nl = tid & 63, kb = tid >> 6;
;   float v[8];
;     ...
;   if (bid_ < ntile) CVT_LOAD(bid_);
; __device__ __forceinline__ void cvt_mixer_b(KP p, int l, LAS unsigned char* lds, int wv0, int f, int st) {
;     ...
;   cvt_job(lds, p->w_o + (size_t)l * DM * DM, (bf16_t*)(W + O_WO), nullptr, DM, DM, DM, 0, wv0, f, st);
.LBB0_496:
	s_mov_b32 s0, -1
	s_and_b64 vcc, exec, s[2:3]
	s_waitcnt vmcnt(0)
	v_mbcnt_lo_u32_b32 v0, s0, 0
	v_mbcnt_hi_u32_b32 v0, s0, v0
	v_or_b32_e32 v8, s30, v0
	s_cbranch_vccnz .LBB0_518
	s_cmpk_gt_u32 s25, 0x3ff
	s_cbranch_scc1 .LBB0_518
	s_load_dwordx2 s[0:1], s[54:55], 0x80
	s_lshl_b64 s[2:3], s[8:9], 2
	v_and_b32_e32 v14, 63, v8
	v_ashrrev_i32_e32 v9, 6, v8
	v_ashrrev_i32_e32 v15, 3, v8
	s_waitcnt lgkmcnt(0)
	s_add_u32 s4, s0, s2
	s_addc_u32 s5, s1, s3
	s_add_u32 s6, s10, 0x4100000
	s_addc_u32 s7, s11, 0
	s_lshl_b32 s0, s25, 6
	s_lshl_b32 s2, s25, 1
	s_and_b32 s1, s0, 0x7c0
	s_and_b32 s2, s2, 0x7c0
	v_or_b32_e32 v1, s2, v14
	v_add_u32_e32 v0, s1, v9
	v_lshlrev_b32_e32 v96, 2, v1
	v_ashrrev_i32_e32 v1, 31, v0
	v_lshl_add_u64 v[2:3], s[4:5], 0, v[96:97]
	v_lshlrev_b64 v[0:1], 13, v[0:1]
	v_lshl_add_u64 v[10:11], v[2:3], 0, v[0:1]
	s_mov_b32 s1, 0x10000
	v_add_co_u32_e32 v2, vcc, s1, v10
	s_mov_b32 s1, 0x20000
	s_nop 0
	v_addc_co_u32_e32 v3, vcc, 0, v11, vcc
	global_load_dword v0, v[10:11], off nt
	global_load_dword v1, v[2:3], off nt
	v_add_co_u32_e32 v2, vcc, s1, v10
	s_mov_b32 s1, 0x30000
	s_nop 0
	v_addc_co_u32_e32 v3, vcc, 0, v11, vcc
	v_add_co_u32_e32 v4, vcc, s1, v10
	s_mov_b32 s1, 0x40000
	s_nop 0
	v_addc_co_u32_e32 v5, vcc, 0, v11, vcc
	global_load_dword v2, v[2:3], off nt
	v_lshlrev_b32_e32 v8, 3, v8
	global_load_dword v3, v[4:5], off nt
	v_add_co_u32_e32 v4, vcc, s1, v10
	s_mov_b32 s1, 0x50000
	s_nop 0
	v_addc_co_u32_e32 v5, vcc, 0, v11, vcc
	v_add_co_u32_e32 v6, vcc, s1, v10
	s_mov_b32 s1, 0x60000
	s_nop 0
	v_addc_co_u32_e32 v7, vcc, 0, v11, vcc
	global_load_dword v4, v[4:5], off nt
	v_and_b32_e32 v8, 56, v8
	global_load_dword v5, v[6:7], off nt
	v_add_co_u32_e32 v6, vcc, s1, v10
	s_mov_b32 s1, 0x70000
	s_nop 0
	v_addc_co_u32_e32 v7, vcc, 0, v11, vcc
	v_add_co_u32_e32 v10, vcc, s1, v10
	global_load_dword v6, v[6:7], off nt
	s_nop 0
	v_addc_co_u32_e32 v11, vcc, 0, v11, vcc
	global_load_dword v7, v[10:11], off nt
	v_lshl_add_u32 v10, v14, 2, 0
	v_lshl_add_u32 v11, v15, 2, 0
	v_mul_u32_u24_e32 v12, 0x104, v8
	v_mul_lo_u32 v13, v9, s70
	s_lshl_b32 s1, s24, 6
	v_add_u32_e32 v16, s1, v9
	v_add_u32_e32 v17, v10, v13
	v_add_u32_e32 v18, v11, v12
	v_lshlrev_b32_e32 v8, 1, v8
	s_branch .LBB0_501

; #define CVT_LOAD(t_) do { const int k0_ = ((t_) % nkt) * 64, n0_ = ((t_) / nkt) * 64; const int sn = srcmap(kind, n0_ + nl); \
;     _Pragma("unroll") for (int i = 0; i < 8; ++i) { const int kl = kb + 8 * i; v[i] = 0.f; \
;       if (sn >= 0) { v[i] = src[(size_t)(k0_ + kl) * Nsrc + sn]; if (kscale) v[i] *= kscale[k0_ + kl]; } } } while (0)
; __device__ __forceinline__ void cvt_job(LAS unsigned char* lds, const float* src, bf16_t* dst, const float* kscale, int K, int Nsrc, int Ndst, int kind, int wv0, int bid_, int grd_) {
;     ...
;   for (int t = bid_; t < ntile; t += grd_) {
;     const int k0 = (t % nkt) * 64, n0 = (t / nkt) * 64;
; #pragma unroll
;     for (int i = 0; i < 8; ++i) tile[(kb + 8 * i) * 65 + nl] = v[i];
;     __syncthreads();
;     if (t + grd_ < ntile) CVT_LOAD(t + grd_);
.LBB0_501:
	s_add_i32 s14, s25, s24
	s_cmpk_gt_i32 s14, 0x3ff
	s_cselect_b64 s[8:9], -1, 0
	s_and_b64 vcc, exec, s[8:9]
	s_waitcnt vmcnt(1)
	ds_write_b32 v17, v0
	s_waitcnt vmcnt(6)
	ds_write_b32 v17, v1 offset:2080
	s_waitcnt vmcnt(5)
	ds_write_b32 v17, v2 offset:4160
	s_waitcnt vmcnt(4)
	ds_write_b32 v17, v3 offset:6240
	s_waitcnt vmcnt(3)
	ds_write_b32 v17, v4 offset:8320
	s_waitcnt vmcnt(2)
	ds_write_b32 v17, v5 offset:10400
	s_waitcnt vmcnt(1)
	ds_write_b32 v17, v6 offset:12480
	s_waitcnt vmcnt(0)
	ds_write_b32 v17, v7 offset:14560
	s_waitcnt lgkmcnt(0)
	s_barrier
	s_cbranch_vccnz .LBB0_500
	s_ashr_i32 s2, s14, 31
	s_lshr_b32 s2, s2, 27
	s_add_i32 s2, s14, s2
	s_ashr_i32 s2, s2, 5
	s_cmpk_gt_i32 s14, 0xffe0
	v_lshl_or_b32 v96, s2, 6, v14
	s_cselect_b64 s[12:13], -1, 0
	s_lshl_b32 s2, s2, 11
	v_add_u32_e32 v0, s0, v16
	s_cmpk_lt_i32 s14, 0xffe1
	v_subrev_u32_e32 v12, s2, v0
	v_lshl_add_u64 v[10:11], v[96:97], 2, s[4:5]
	v_mov_b32_e32 v0, s93
	s_cbranch_scc1 .LBB0_504
	v_ashrrev_i32_e32 v13, 31, v12
	v_lshlrev_b64 v[0:1], 13, v[12:13]
	v_lshl_add_u64 v[0:1], v[10:11], 0, v[0:1]
	global_load_dword v0, v[0:1], off nt
.LBB0_504:
	v_cndmask_b32_e64 v2, 0, 1, s[12:13]
	v_cmp_ne_u32_e64 s[2:3], 1, v2
	s_andn2_b64 vcc, exec, s[12:13]
	s_cbranch_vccnz .LBB0_511
	v_add_u32_e32 v2, 8, v12
	v_ashrrev_i32_e32 v3, 31, v2
	v_lshlrev_b64 v[2:3], 13, v[2:3]
	v_lshl_add_u64 v[2:3], v[10:11], 0, v[2:3]
	global_load_dword v1, v[2:3], off nt
	s_and_b64 vcc, exec, s[2:3]
	s_cbranch_vccz .LBB0_512

.LBB0_512:
	v_add_u32_e32 v2, 16, v12
	v_ashrrev_i32_e32 v3, 31, v2
	v_lshlrev_b64 v[2:3], 13, v[2:3]
	v_lshl_add_u64 v[2:3], v[10:11], 0, v[2:3]
	global_load_dword v2, v[2:3], off nt
	s_and_b64 vcc, exec, s[2:3]
	s_cbranch_vccnz .LBB0_507
.LBB0_513:
	v_add_u32_e32 v4, 24, v12
	v_ashrrev_i32_e32 v5, 31, v4
	v_lshlrev_b64 v[4:5], 13, v[4:5]
	v_lshl_add_u64 v[4:5], v[10:11], 0, v[4:5]
	global_load_dword v3, v[4:5], off nt
	s_and_b64 vcc, exec, s[2:3]
	s_cbranch_vccnz .LBB0_508
.LBB0_514:
	v_add_u32_e32 v4, 32, v12
	v_ashrrev_i32_e32 v5, 31, v4
	v_lshlrev_b64 v[4:5], 13, v[4:5]
	v_lshl_add_u64 v[4:5], v[10:11], 0, v[4:5]
	global_load_dword v4, v[4:5], off nt
	s_and_b64 vcc, exec, s[2:3]
	s_cbranch_vccnz .LBB0_509
.LBB0_515:
	v_add_u32_e32 v6, 40, v12
	v_ashrrev_i32_e32 v7, 31, v6
	v_lshlrev_b64 v[6:7], 13, v[6:7]
	v_lshl_add_u64 v[6:7], v[10:11], 0, v[6:7]
	global_load_dword v5, v[6:7], off nt
	s_and_b64 vcc, exec, s[2:3]
	s_cbranch_vccnz .LBB0_510
.LBB0_516:
	v_add_u32_e32 v6, 48, v12
	v_ashrrev_i32_e32 v7, 31, v6
	v_lshlrev_b64 v[6:7], 13, v[6:7]
	v_lshl_add_u64 v[6:7], v[10:11], 0, v[6:7]
	global_load_dword v6, v[6:7], off nt
	s_and_b64 vcc, exec, s[2:3]
	s_cbranch_vccz .LBB0_499

;   __device__ __forceinline__ void preload(EpiPre& q, int row, int col) const {
;     ...
;     } else if (MODE == E_RES) {
;       const float* rs = e.f0 + (size_t)row * DM + col; q.a0 = *(const f32x4*)rs; q.a1 = *(const f32x4*)(rs + 4);
;   __device__ __forceinline__ void emit(const EpiPre& q0, int row, int col, f32x4 a, f32x4 b, const f32x4 (&hb)[2][2], const float (&hs)[2][4], int ai_, int m_, int bj_) const {
;     ...
;     } else if (MODE == E_RES) {
;       const f32x4 r0 = q.a0, r1 = q.a1;
;       float* o = (float*)e.out + (size_t)row * DM + col;
;       *(f32x4*)o = (f32x4){ALPHA * r0[0] + v[0], ALPHA * r0[1] + v[1], ALPHA * r0[2] + v[2], ALPHA * r0[3] + v[3]};
;       *(f32x4*)(o + 4) = (f32x4){ALPHA * r1[0] + v[4], ALPHA * r1[1] + v[5], ALPHA * r1[2] + v[6], ALPHA * r1[3] + v[7]};
.Lwo_plain:
	v_lshl_add_u32 v172, s18, 8, v184
	v_lshl_or_b32 v180, s1, 8, v186
	v_lshlrev_b32_e32 v172, 13, v172
	v_lshl_add_u32 v172, v180, 2, v172
	global_load_dwordx4 v[130:133], v172, s[8:9] nt
	global_load_dwordx4 v[134:137], v172, s[8:9] offset:16 nt
	global_load_dwordx4 v[138:141], v172, s[8:9] offset:512 nt
	global_load_dwordx4 v[142:145], v172, s[8:9] offset:528 nt
	v_add_u32_e32 v173, 0x20000, v172
	global_load_dwordx4 v[146:149], v173, s[8:9] nt
	global_load_dwordx4 v[150:153], v173, s[8:9] offset:16 nt
	global_load_dwordx4 v[154:157], v173, s[8:9] offset:512 nt
	global_load_dwordx4 v[158:161], v173, s[8:9] offset:528 nt
	v_add_u32_e32 v174, 0x40000, v172
	global_load_dwordx4 v[188:191], v174, s[8:9] nt
	global_load_dwordx4 v[192:195], v174, s[8:9] offset:16 nt
	global_load_dwordx4 v[196:199], v174, s[8:9] offset:512 nt
	global_load_dwordx4 v[200:203], v174, s[8:9] offset:528 nt
	v_add_u32_e32 v175, 0x60000, v172
	global_load_dwordx4 v[204:207], v175, s[8:9] nt
	global_load_dwordx4 v[208:211], v175, s[8:9] offset:16 nt
	global_load_dwordx4 v[212:215], v175, s[8:9] offset:512 nt
	global_load_dwordx4 v[216:219], v175, s[8:9] offset:528 nt
	v_add_u32_e32 v176, 0x100000, v172
	v_add_u32_e32 v177, 0x120000, v172
	v_add_u32_e32 v178, 0x140000, v172
	v_add_u32_e32 v179, 0x160000, v172
	s_waitcnt vmcnt(12)
	v_pk_fma_f32 v[126:127], v[130:131], s[90:91], v[126:127] op_sel_hi:[1,0,1]
	v_pk_fma_f32 v[128:129], v[132:133], s[90:91], v[128:129] op_sel_hi:[1,0,1]
	v_pk_fma_f32 v[122:123], v[134:135], s[90:91], v[122:123] op_sel_hi:[1,0,1]
	v_pk_fma_f32 v[124:125], v[136:137], s[90:91], v[124:125] op_sel_hi:[1,0,1]
	v_pk_fma_f32 v[110:111], v[138:139], s[90:91], v[110:111] op_sel_hi:[1,0,1]
	v_pk_fma_f32 v[112:113], v[140:141], s[90:91], v[112:113] op_sel_hi:[1,0,1]
	v_pk_fma_f32 v[106:107], v[142:143], s[90:91], v[106:107] op_sel_hi:[1,0,1]
	v_pk_fma_f32 v[108:109], v[144:145], s[90:91], v[108:109] op_sel_hi:[1,0,1]
	global_load_dwordx4 v[130:133], v176, s[8:9] nt
	global_load_dwordx4 v[134:137], v176, s[8:9] offset:16 nt
	global_load_dwordx4 v[138:141], v176, s[8:9] offset:512 nt
	global_load_dwordx4 v[142:145], v176, s[8:9] offset:528 nt
	s_waitcnt vmcnt(12)
	v_pk_fma_f32 v[118:119], v[146:147], s[90:91], v[118:119] op_sel_hi:[1,0,1]
	v_pk_fma_f32 v[120:121], v[148:149], s[90:91], v[120:121] op_sel_hi:[1,0,1]
	v_pk_fma_f32 v[114:115], v[150:151], s[90:91], v[114:115] op_sel_hi:[1,0,1]
	v_pk_fma_f32 v[116:117], v[152:153], s[90:91], v[116:117] op_sel_hi:[1,0,1]
	v_pk_fma_f32 v[102:103], v[154:155], s[90:91], v[102:103] op_sel_hi:[1,0,1]
	v_pk_fma_f32 v[104:105], v[156:157], s[90:91], v[104:105] op_sel_hi:[1,0,1]
	v_pk_fma_f32 v[98:99], v[158:159], s[90:91], v[98:99] op_sel_hi:[1,0,1]
	v_pk_fma_f32 v[100:101], v[160:161], s[90:91], v[100:101] op_sel_hi:[1,0,1]
	global_load_dwordx4 v[146:149], v177, s[8:9] nt
	global_load_dwordx4 v[150:153], v177, s[8:9] offset:16 nt
	global_load_dwordx4 v[154:157], v177, s[8:9] offset:512 nt
	global_load_dwordx4 v[158:161], v177, s[8:9] offset:528 nt
	s_waitcnt vmcnt(12)
	v_pk_fma_f32 v[92:93], v[188:189], s[90:91], v[92:93] op_sel_hi:[1,0,1]
	v_pk_fma_f32 v[94:95], v[190:191], s[90:91], v[94:95] op_sel_hi:[1,0,1]
	v_pk_fma_f32 v[88:89], v[192:193], s[90:91], v[88:89] op_sel_hi:[1,0,1]
	v_pk_fma_f32 v[90:91], v[194:195], s[90:91], v[90:91] op_sel_hi:[1,0,1]
	v_pk_fma_f32 v[80:81], v[196:197], s[90:91], v[80:81] op_sel_hi:[1,0,1]
	v_pk_fma_f32 v[82:83], v[198:199], s[90:91], v[82:83] op_sel_hi:[1,0,1]
	v_pk_fma_f32 v[72:73], v[200:201], s[90:91], v[72:73] op_sel_hi:[1,0,1]
	v_pk_fma_f32 v[74:75], v[202:203], s[90:91], v[74:75] op_sel_hi:[1,0,1]
	global_load_dwordx4 v[188:191], v178, s[8:9] nt
	global_load_dwordx4 v[192:195], v178, s[8:9] offset:16 nt
	global_load_dwordx4 v[196:199], v178, s[8:9] offset:512 nt
	global_load_dwordx4 v[200:203], v178, s[8:9] offset:528 nt
	s_waitcnt vmcnt(12)
;   __device__ __forceinline__ void emit(const EpiPre& q0, int row, int col, f32x4 a, f32x4 b, const f32x4 (&hb)[2][2], const float (&hs)[2][4], int ai_, int m_, int bj_) const {
;     ...
;     } else if (MODE == E_RES) {
;       const f32x4 r0 = q.a0, r1 = q.a1;
;       float* o = (float*)e.out + (size_t)row * DM + col;
;       *(f32x4*)o = (f32x4){ALPHA * r0[0] + v[0], ALPHA * r0[1] + v[1], ALPHA * r0[2] + v[2], ALPHA * r0[3] + v[3]};
;       *(f32x4*)(o + 4) = (f32x4){ALPHA * r1[0] + v[4], ALPHA * r1[1] + v[5], ALPHA * r1[2] + v[6], ALPHA * r1[3] + v[7]};
	v_pk_fma_f32 v[84:85], v[204:205], s[90:91], v[84:85] op_sel_hi:[1,0,1]
	v_pk_fma_f32 v[86:87], v[206:207], s[90:91], v[86:87] op_sel_hi:[1,0,1]
	v_pk_fma_f32 v[76:77], v[208:209], s[90:91], v[76:77] op_sel_hi:[1,0,1]
	v_pk_fma_f32 v[78:79], v[210:211], s[90:91], v[78:79] op_sel_hi:[1,0,1]
	v_pk_fma_f32 v[68:69], v[212:213], s[90:91], v[68:69] op_sel_hi:[1,0,1]
	v_pk_fma_f32 v[70:71], v[214:215], s[90:91], v[70:71] op_sel_hi:[1,0,1]
	v_pk_fma_f32 v[64:65], v[216:217], s[90:91], v[64:65] op_sel_hi:[1,0,1]
	v_pk_fma_f32 v[66:67], v[218:219], s[90:91], v[66:67] op_sel_hi:[1,0,1]
	global_load_dwordx4 v[204:207], v179, s[8:9] nt
	global_load_dwordx4 v[208:211], v179, s[8:9] offset:16 nt
	global_load_dwordx4 v[212:215], v179, s[8:9] offset:512 nt
	global_load_dwordx4 v[216:219], v179, s[8:9] offset:528 nt
	global_store_dwordx4 v172, v[126:129], s[6:7]
	global_store_dwordx4 v172, v[122:125], s[6:7] offset:16
	global_store_dwordx4 v172, v[110:113], s[6:7] offset:512
	global_store_dwordx4 v172, v[106:109], s[6:7] offset:528
	global_store_dwordx4 v173, v[118:121], s[6:7]
	global_store_dwordx4 v173, v[114:117], s[6:7] offset:16
	global_store_dwordx4 v173, v[102:105], s[6:7] offset:512
	global_store_dwordx4 v173, v[98:101], s[6:7] offset:528
	global_store_dwordx4 v174, v[92:95], s[6:7]
	global_store_dwordx4 v174, v[88:91], s[6:7] offset:16
	global_store_dwordx4 v174, v[80:83], s[6:7] offset:512
	global_store_dwordx4 v174, v[72:75], s[6:7] offset:528
	global_store_dwordx4 v175, v[84:87], s[6:7]
	global_store_dwordx4 v175, v[76:79], s[6:7] offset:16
	global_store_dwordx4 v175, v[68:71], s[6:7] offset:512
	global_store_dwordx4 v175, v[64:67], s[6:7] offset:528
	s_waitcnt vmcnt(28)
	v_pk_fma_f32 v[60:61], v[130:131], s[90:91], v[60:61] op_sel_hi:[1,0,1]
	v_pk_fma_f32 v[62:63], v[132:133], s[90:91], v[62:63] op_sel_hi:[1,0,1]
	v_pk_fma_f32 v[56:57], v[134:135], s[90:91], v[56:57] op_sel_hi:[1,0,1]
	v_pk_fma_f32 v[58:59], v[136:137], s[90:91], v[58:59] op_sel_hi:[1,0,1]
	v_pk_fma_f32 v[52:53], v[138:139], s[90:91], v[52:53] op_sel_hi:[1,0,1]
	v_pk_fma_f32 v[54:55], v[140:141], s[90:91], v[54:55] op_sel_hi:[1,0,1]
	v_pk_fma_f32 v[48:49], v[142:143], s[90:91], v[48:49] op_sel_hi:[1,0,1]
	v_pk_fma_f32 v[50:51], v[144:145], s[90:91], v[50:51] op_sel_hi:[1,0,1]
	global_store_dwordx4 v176, v[60:63], s[6:7]
	global_store_dwordx4 v176, v[56:59], s[6:7] offset:16
	global_store_dwordx4 v176, v[52:55], s[6:7] offset:512
	global_store_dwordx4 v176, v[48:51], s[6:7] offset:528
	s_waitcnt vmcnt(28)
	v_pk_fma_f32 v[44:45], v[146:147], s[90:91], v[44:45] op_sel_hi:[1,0,1]
	v_pk_fma_f32 v[46:47], v[148:149], s[90:91], v[46:47] op_sel_hi:[1,0,1]
	v_pk_fma_f32 v[40:41], v[150:151], s[90:91], v[40:41] op_sel_hi:[1,0,1]
	v_pk_fma_f32 v[42:43], v[152:153], s[90:91], v[42:43] op_sel_hi:[1,0,1]
	v_pk_fma_f32 v[36:37], v[154:155], s[90:91], v[36:37] op_sel_hi:[1,0,1]
	v_pk_fma_f32 v[38:39], v[156:157], s[90:91], v[38:39] op_sel_hi:[1,0,1]
	v_pk_fma_f32 v[32:33], v[158:159], s[90:91], v[32:33] op_sel_hi:[1,0,1]
	v_pk_fma_f32 v[34:35], v[160:161], s[90:91], v[34:35] op_sel_hi:[1,0,1]
	global_store_dwordx4 v177, v[44:47], s[6:7]
	global_store_dwordx4 v177, v[40:43], s[6:7] offset:16
	global_store_dwordx4 v177, v[36:39], s[6:7] offset:512
	global_store_dwordx4 v177, v[32:35], s[6:7] offset:528
	s_waitcnt vmcnt(28)
	v_pk_fma_f32 v[28:29], v[188:189], s[90:91], v[28:29] op_sel_hi:[1,0,1]
	v_pk_fma_f32 v[30:31], v[190:191], s[90:91], v[30:31] op_sel_hi:[1,0,1]
	v_pk_fma_f32 v[24:25], v[192:193], s[90:91], v[24:25] op_sel_hi:[1,0,1]
	v_pk_fma_f32 v[26:27], v[194:195], s[90:91], v[26:27] op_sel_hi:[1,0,1]
	v_pk_fma_f32 v[16:17], v[196:197], s[90:91], v[16:17] op_sel_hi:[1,0,1]
	v_pk_fma_f32 v[18:19], v[198:199], s[90:91], v[18:19] op_sel_hi:[1,0,1]
	v_pk_fma_f32 v[12:13], v[200:201], s[90:91], v[12:13] op_sel_hi:[1,0,1]
	v_pk_fma_f32 v[14:15], v[202:203], s[90:91], v[14:15] op_sel_hi:[1,0,1]
	global_store_dwordx4 v178, v[28:31], s[6:7]
	global_store_dwordx4 v178, v[24:27], s[6:7] offset:16
	global_store_dwordx4 v178, v[16:19], s[6:7] offset:512
	global_store_dwordx4 v178, v[12:15], s[6:7] offset:528
	s_waitcnt vmcnt(28)
	v_pk_fma_f32 v[20:21], v[204:205], s[90:91], v[20:21] op_sel_hi:[1,0,1]
	v_pk_fma_f32 v[22:23], v[206:207], s[90:91], v[22:23] op_sel_hi:[1,0,1]
	v_pk_fma_f32 v[8:9], v[208:209], s[90:91], v[8:9] op_sel_hi:[1,0,1]
	v_pk_fma_f32 v[10:11], v[210:211], s[90:91], v[10:11] op_sel_hi:[1,0,1]
	v_pk_fma_f32 v[4:5], v[212:213], s[90:91], v[4:5] op_sel_hi:[1,0,1]
	v_pk_fma_f32 v[6:7], v[214:215], s[90:91], v[6:7] op_sel_hi:[1,0,1]
	v_pk_fma_f32 v[0:1], v[216:217], s[90:91], v[0:1] op_sel_hi:[1,0,1]
	v_pk_fma_f32 v[2:3], v[218:219], s[90:91], v[2:3] op_sel_hi:[1,0,1]
	global_store_dwordx4 v179, v[20:23], s[6:7]
	global_store_dwordx4 v179, v[8:11], s[6:7] offset:16
	global_store_dwordx4 v179, v[4:7], s[6:7] offset:512
	global_store_dwordx4 v179, v[0:3], s[6:7] offset:528
	s_mov_b32 s18, s12
	s_mov_b64 s[22:23], s[16:17]
	s_mov_b64 s[20:21], s[14:15]
	s_and_b64 vcc, exec, s[2:3]
	s_mov_b32 s1, s10
